# ssd3 gate/combine: the 16 x/z loads of each row block issued together (moves behind counted vmcnt)
# baseline (speedup 1.0000x reference)
.LBB0_125:
	v_readlane_b32 s0, v251, 2
	v_lshlrev_b32_e32 v66, 2, v162
	v_readlane_b32 s4, v251, 6
	v_readlane_b32 s5, v251, 7
	s_barrier
	s_nop 3
	global_load_dword v67, v66, s[4:5]
	s_nop 0
	global_load_dword v66, v66, s[4:5] offset:128
	v_readlane_b32 s1, v251, 3
	v_readlane_b32 s2, v251, 4
	v_readlane_b32 s3, v251, 5
	v_readlane_b32 s0, v255, 14
	v_readlane_b32 s1, v255, 15
	v_readlane_b32 s50, v255, 16
	v_readlane_b32 s2, v255, 8
	s_lshl_b64 s[0:1], s[0:1], 14
	v_readlane_b32 s51, v255, 17
	v_readlane_b32 s38, v254, 57
	v_ashrrev_i32_e32 v83, 31, v82
	v_readlane_b32 s3, v255, 9
	s_or_b64 s[0:1], s[50:51], s[0:1]
	v_readlane_b32 s39, v254, 58
	v_readlane_b32 s64, v254, 55
	v_lshl_add_u64 v[68:69], s[2:3], 0, v[82:83]
	v_readlane_b32 s65, v254, 56
	v_lshl_add_u64 v[70:71], s[0:1], 0, v[82:83]
	v_lshlrev_b64 v[68:69], 13, v[68:69]
	v_readlane_b32 s8, v251, 10
	v_readlane_b32 s9, v251, 11
	v_readlane_b32 s8, v255, 12
	v_readlane_b32 s9, v255, 13
	v_readlane_b32 s6, v251, 8
	v_readlane_b32 s7, v251, 9
	v_readlane_b32 s10, v251, 12
	v_readlane_b32 s11, v251, 13
	v_readlane_b32 s12, v251, 14
	v_readlane_b32 s13, v251, 15
	v_readlane_b32 s14, v251, 16
	v_readlane_b32 s15, v251, 17
	s_waitcnt vmcnt(0)
	v_add_f32_e32 v72, v67, v66
	v_lshlrev_b32_e32 v66, 7, v162
	v_mov_b32_e32 v67, v1
	v_lshl_add_u64 v[74:75], s[38:39], 0, v[66:67]
	v_lshl_add_u64 v[66:67], s[64:65], 0, v[66:67]
	v_lshl_add_u64 v[76:77], v[74:75], 0, v[68:69]
	v_lshlrev_b64 v[68:69], 12, v[70:71]
	v_lshl_add_u64 v[70:71], v[66:67], 0, v[68:69]
	v_lshlrev_b32_e32 v68, 1, v150
	v_mov_b32_e32 v69, v1
	v_lshl_add_u64 v[94:95], v[76:77], 0, v[68:69]
	v_lshl_add_u64 v[88:89], v[70:71], 0, v[68:69]
	global_load_dwordx2 v[200:201], v[94:95], off
	global_load_dwordx2 v[202:203], v[88:89], off
	global_load_dwordx2 v[204:205], v[94:95], off offset:16
	global_load_dwordx2 v[206:207], v[88:89], off offset:16
	global_load_dwordx2 v[208:209], v[94:95], off offset:32
	global_load_dwordx2 v[210:211], v[88:89], off offset:32
	global_load_dwordx2 v[212:213], v[94:95], off offset:48
	global_load_dwordx2 v[214:215], v[88:89], off offset:48
	global_load_dwordx2 v[222:223], v[94:95], off offset:64
	global_load_dwordx2 v[224:225], v[88:89], off offset:64
	global_load_dwordx2 v[226:227], v[94:95], off offset:80
	global_load_dwordx2 v[228:229], v[88:89], off offset:80
	global_load_dwordx2 v[130:131], v[94:95], off offset:96
	global_load_dwordx2 v[132:133], v[88:89], off offset:96
	global_load_dwordx2 v[134:135], v[94:95], off offset:112
	global_load_dwordx2 v[136:137], v[88:89], off offset:112
	s_waitcnt vmcnt(15)
	v_mov_b32_e32 v78, v200
	v_mov_b32_e32 v79, v201
	v_and_b32_e32 v71, 0xffff0000, v78
	s_waitcnt vmcnt(14)
	v_mov_b32_e32 v80, v202
	v_mov_b32_e32 v81, v203
	v_lshlrev_b32_e32 v76, 16, v80
	v_mul_f32_e32 v73, 0xbfb8aa3b, v76
	v_exp_f32_e32 v73, v73
	v_lshlrev_b32_e32 v70, 16, v78
	v_and_b32_e32 v77, 0xffff0000, v80
	v_lshlrev_b32_e32 v78, 16, v81
	v_add_f32_e32 v73, 1.0, v73
	v_pk_fma_f32 v[50:51], v[72:73], v[70:71], v[50:51] op_sel_hi:[0,1,1]
	v_mul_f32_e32 v70, 0xbfb8aa3b, v77
	v_exp_f32_e32 v70, v70
	v_rcp_f32_e32 v82, v73
	v_mul_f32_e32 v73, 0xbfb8aa3b, v78
	v_exp_f32_e32 v73, v73
	v_add_f32_e32 v70, 1.0, v70
	v_rcp_f32_e32 v83, v70
	v_add_f32_e32 v73, 1.0, v73
	v_rcp_f32_e32 v80, v73
	v_pk_mul_f32 v[70:71], v[82:83], v[76:77]
	s_nop 0
	v_pk_mul_f32 v[70:71], v[50:51], v[70:71]
	v_and_b32_e32 v51, 0xffff0000, v79
	v_lshlrev_b32_e32 v50, 16, v79
	v_and_b32_e32 v79, 0xffff0000, v81
	v_pk_fma_f32 v[50:51], v[72:73], v[50:51], v[52:53] op_sel_hi:[0,1,1]
	v_mul_f32_e32 v52, 0xbfb8aa3b, v79
	v_exp_f32_e32 v52, v52
	v_pk_mul_f32 v[76:77], v[70:71], v[70:71]
	v_add_f32_e32 v52, 1.0, v52
	v_rcp_f32_e32 v81, v52
	s_nop 0
	v_pk_mul_f32 v[52:53], v[80:81], v[78:79]
	s_nop 0
	v_pk_mul_f32 v[50:51], v[50:51], v[52:53]
	v_pk_mul_f32 v[78:79], v[50:51], v[50:51]
	s_waitcnt vmcnt(13)
	v_mov_b32_e32 v52, v204
	v_mov_b32_e32 v53, v205
	v_and_b32_e32 v81, 0xffff0000, v52
	s_waitcnt vmcnt(12)
	v_mov_b32_e32 v82, v206
	v_mov_b32_e32 v83, v207
	v_lshlrev_b32_e32 v84, 16, v82
	v_lshlrev_b32_e32 v80, 16, v52
	v_mul_f32_e32 v52, 0xbfb8aa3b, v84
	v_exp_f32_e32 v52, v52
	v_and_b32_e32 v85, 0xffff0000, v82
	v_pk_fma_f32 v[54:55], v[72:73], v[80:81], v[54:55] op_sel_hi:[0,1,1]
	v_add_f32_e32 v52, 1.0, v52
	v_rcp_f32_e32 v86, v52
	v_mul_f32_e32 v52, 0xbfb8aa3b, v85
	v_exp_f32_e32 v52, v52
	s_nop 0
	v_add_f32_e32 v52, 1.0, v52
	v_rcp_f32_e32 v87, v52
	v_lshlrev_b32_e32 v52, 16, v83
	v_mul_f32_e32 v73, 0xbfb8aa3b, v52
	v_exp_f32_e32 v73, v73
	v_pk_mul_f32 v[80:81], v[86:87], v[84:85]
	v_and_b32_e32 v85, 0xffff0000, v53
	v_lshlrev_b32_e32 v84, 16, v53
	v_and_b32_e32 v53, 0xffff0000, v83
	v_add_f32_e32 v73, 1.0, v73
	v_rcp_f32_e32 v82, v73
	v_pk_fma_f32 v[56:57], v[72:73], v[84:85], v[56:57] op_sel_hi:[0,1,1]
	v_mul_f32_e32 v73, 0xbfb8aa3b, v53
	v_exp_f32_e32 v73, v73
	v_pk_mul_f32 v[54:55], v[54:55], v[80:81]
	v_add_f32_e32 v73, 1.0, v73
	v_rcp_f32_e32 v83, v73
	v_pk_mul_f32 v[80:81], v[54:55], v[54:55]
	v_pk_mul_f32 v[52:53], v[82:83], v[52:53]
	s_nop 0
	v_pk_mul_f32 v[52:53], v[56:57], v[52:53]
	v_pk_mul_f32 v[82:83], v[52:53], v[52:53]
	s_waitcnt vmcnt(11)
	v_mov_b32_e32 v56, v208
	v_mov_b32_e32 v57, v209
	v_and_b32_e32 v85, 0xffff0000, v56
	s_waitcnt vmcnt(10)
	v_mov_b32_e32 v86, v210
	v_mov_b32_e32 v87, v211
	v_lshlrev_b32_e32 v90, 16, v86
	v_lshlrev_b32_e32 v84, 16, v56
	v_mul_f32_e32 v56, 0xbfb8aa3b, v90
	v_exp_f32_e32 v56, v56
	v_and_b32_e32 v91, 0xffff0000, v86
	v_pk_fma_f32 v[58:59], v[72:73], v[84:85], v[58:59] op_sel_hi:[0,1,1]
	v_add_f32_e32 v56, 1.0, v56
	v_rcp_f32_e32 v92, v56
	v_mul_f32_e32 v56, 0xbfb8aa3b, v91
	v_exp_f32_e32 v56, v56
	s_nop 0
	v_add_f32_e32 v56, 1.0, v56
	v_rcp_f32_e32 v93, v56
	v_lshlrev_b32_e32 v56, 16, v87
	v_mul_f32_e32 v73, 0xbfb8aa3b, v56
	v_exp_f32_e32 v73, v73
	v_pk_mul_f32 v[84:85], v[92:93], v[90:91]
	v_and_b32_e32 v91, 0xffff0000, v57
	v_lshlrev_b32_e32 v90, 16, v57
	v_and_b32_e32 v57, 0xffff0000, v87
	v_add_f32_e32 v73, 1.0, v73
	v_rcp_f32_e32 v86, v73
	v_pk_fma_f32 v[60:61], v[72:73], v[90:91], v[60:61] op_sel_hi:[0,1,1]
	v_mul_f32_e32 v73, 0xbfb8aa3b, v57
	v_exp_f32_e32 v73, v73
	v_pk_mul_f32 v[58:59], v[58:59], v[84:85]
	v_add_f32_e32 v73, 1.0, v73
	v_rcp_f32_e32 v87, v73
	v_pk_mul_f32 v[84:85], v[58:59], v[58:59]
	v_pk_mul_f32 v[56:57], v[86:87], v[56:57]
	s_nop 0
	v_pk_mul_f32 v[56:57], v[60:61], v[56:57]
	v_pk_mul_f32 v[86:87], v[56:57], v[56:57]
	s_waitcnt vmcnt(9)
	v_mov_b32_e32 v60, v212
	v_mov_b32_e32 v61, v213
	v_and_b32_e32 v91, 0xffff0000, v60
	s_waitcnt vmcnt(8)
	v_mov_b32_e32 v92, v214
	v_mov_b32_e32 v93, v215
	v_lshlrev_b32_e32 v96, 16, v92
	v_lshlrev_b32_e32 v90, 16, v60
	v_mul_f32_e32 v60, 0xbfb8aa3b, v96
	v_exp_f32_e32 v60, v60
	v_and_b32_e32 v97, 0xffff0000, v92
	v_pk_fma_f32 v[62:63], v[72:73], v[90:91], v[62:63] op_sel_hi:[0,1,1]
	v_add_f32_e32 v60, 1.0, v60
	v_rcp_f32_e32 v98, v60
	v_mul_f32_e32 v60, 0xbfb8aa3b, v97
	v_exp_f32_e32 v60, v60
	s_nop 0
	v_add_f32_e32 v60, 1.0, v60
	v_rcp_f32_e32 v99, v60
	v_lshlrev_b32_e32 v60, 16, v93
	v_mul_f32_e32 v73, 0xbfb8aa3b, v60
	v_exp_f32_e32 v73, v73
	v_pk_mul_f32 v[90:91], v[98:99], v[96:97]
	v_and_b32_e32 v97, 0xffff0000, v61
	v_lshlrev_b32_e32 v96, 16, v61
	v_and_b32_e32 v61, 0xffff0000, v93
	v_add_f32_e32 v73, 1.0, v73
	v_rcp_f32_e32 v92, v73
	v_pk_fma_f32 v[64:65], v[72:73], v[96:97], v[64:65] op_sel_hi:[0,1,1]
	v_mul_f32_e32 v73, 0xbfb8aa3b, v61
	v_exp_f32_e32 v73, v73
	v_pk_mul_f32 v[62:63], v[62:63], v[90:91]
	v_add_f32_e32 v73, 1.0, v73
	v_rcp_f32_e32 v93, v73
	v_pk_mul_f32 v[90:91], v[62:63], v[62:63]
	v_pk_mul_f32 v[60:61], v[92:93], v[60:61]
	s_nop 0
	v_pk_mul_f32 v[60:61], v[64:65], v[60:61]
	s_waitcnt vmcnt(7)
	v_mov_b32_e32 v98, v222
	v_mov_b32_e32 v99, v223
	v_and_b32_e32 v65, 0xffff0000, v98
	s_waitcnt vmcnt(6)
	v_mov_b32_e32 v100, v224
	v_mov_b32_e32 v101, v225
	v_lshlrev_b32_e32 v96, 16, v100
	v_mul_f32_e32 v73, 0xbfb8aa3b, v96
	v_exp_f32_e32 v73, v73
	v_lshlrev_b32_e32 v64, 16, v98
	v_and_b32_e32 v97, 0xffff0000, v100
	v_lshlrev_b32_e32 v98, 16, v101
	v_add_f32_e32 v73, 1.0, v73
	v_pk_fma_f32 v[34:35], v[72:73], v[64:65], v[34:35] op_sel_hi:[0,1,1]
	v_mul_f32_e32 v64, 0xbfb8aa3b, v97
	v_exp_f32_e32 v64, v64
	v_rcp_f32_e32 v102, v73
	v_mul_f32_e32 v73, 0xbfb8aa3b, v98
	v_exp_f32_e32 v73, v73
	v_add_f32_e32 v64, 1.0, v64
	v_rcp_f32_e32 v103, v64
	v_pk_mul_f32 v[92:93], v[60:61], v[60:61]
	v_add_f32_e32 v73, 1.0, v73
	v_rcp_f32_e32 v100, v73
	v_pk_mul_f32 v[64:65], v[102:103], v[96:97]
	s_nop 0
	v_pk_mul_f32 v[64:65], v[34:35], v[64:65]
	v_and_b32_e32 v35, 0xffff0000, v99
	v_lshlrev_b32_e32 v34, 16, v99
	v_and_b32_e32 v99, 0xffff0000, v101
	v_pk_fma_f32 v[34:35], v[72:73], v[34:35], v[36:37] op_sel_hi:[0,1,1]
	v_mul_f32_e32 v36, 0xbfb8aa3b, v99
	v_exp_f32_e32 v36, v36
	v_pk_mul_f32 v[96:97], v[64:65], v[64:65]
	v_add_f32_e32 v36, 1.0, v36
	v_rcp_f32_e32 v101, v36
	s_nop 0
	v_pk_mul_f32 v[36:37], v[100:101], v[98:99]
	s_nop 0
	v_pk_mul_f32 v[34:35], v[34:35], v[36:37]
	v_pk_mul_f32 v[98:99], v[34:35], v[34:35]
	s_waitcnt vmcnt(5)
	v_mov_b32_e32 v36, v226
	v_mov_b32_e32 v37, v227
	v_and_b32_e32 v101, 0xffff0000, v36
	s_waitcnt vmcnt(4)
	v_mov_b32_e32 v102, v228
	v_mov_b32_e32 v103, v229
	v_lshlrev_b32_e32 v104, 16, v102
	v_lshlrev_b32_e32 v100, 16, v36
	v_mul_f32_e32 v36, 0xbfb8aa3b, v104
	v_exp_f32_e32 v36, v36
	v_and_b32_e32 v105, 0xffff0000, v102
	v_pk_fma_f32 v[38:39], v[72:73], v[100:101], v[38:39] op_sel_hi:[0,1,1]
	v_add_f32_e32 v36, 1.0, v36
	v_rcp_f32_e32 v106, v36
	v_mul_f32_e32 v36, 0xbfb8aa3b, v105
	v_exp_f32_e32 v36, v36
	s_nop 0
	v_add_f32_e32 v36, 1.0, v36
	v_rcp_f32_e32 v107, v36
	v_lshlrev_b32_e32 v36, 16, v103
	v_mul_f32_e32 v73, 0xbfb8aa3b, v36
	v_exp_f32_e32 v73, v73
	v_pk_mul_f32 v[100:101], v[106:107], v[104:105]
	v_and_b32_e32 v105, 0xffff0000, v37
	v_lshlrev_b32_e32 v104, 16, v37
	v_and_b32_e32 v37, 0xffff0000, v103
	v_add_f32_e32 v73, 1.0, v73
	v_rcp_f32_e32 v102, v73
	v_pk_fma_f32 v[40:41], v[72:73], v[104:105], v[40:41] op_sel_hi:[0,1,1]
	v_mul_f32_e32 v73, 0xbfb8aa3b, v37
	v_exp_f32_e32 v73, v73
	v_pk_mul_f32 v[38:39], v[38:39], v[100:101]
	v_add_f32_e32 v73, 1.0, v73
	v_rcp_f32_e32 v103, v73
	v_pk_mul_f32 v[100:101], v[38:39], v[38:39]
	v_pk_mul_f32 v[36:37], v[102:103], v[36:37]
	s_nop 0
	v_pk_mul_f32 v[36:37], v[40:41], v[36:37]
	s_nop 0
	s_nop 0
	v_pk_mul_f32 v[102:103], v[36:37], v[36:37]
	s_waitcnt vmcnt(3)
	v_mov_b32_e32 v40, v130
	v_mov_b32_e32 v41, v131
	v_and_b32_e32 v105, 0xffff0000, v40
	s_waitcnt vmcnt(2)
	v_mov_b32_e32 v106, v132
	v_mov_b32_e32 v107, v133
	v_lshlrev_b32_e32 v110, 16, v106
	v_lshlrev_b32_e32 v104, 16, v40
	v_mul_f32_e32 v40, 0xbfb8aa3b, v110
	v_exp_f32_e32 v40, v40
	v_and_b32_e32 v111, 0xffff0000, v106
	v_pk_fma_f32 v[42:43], v[72:73], v[104:105], v[42:43] op_sel_hi:[0,1,1]
	v_add_f32_e32 v40, 1.0, v40
	v_rcp_f32_e32 v112, v40
	v_mul_f32_e32 v40, 0xbfb8aa3b, v111
	v_exp_f32_e32 v40, v40
	s_nop 0
	v_add_f32_e32 v40, 1.0, v40
	v_rcp_f32_e32 v113, v40
	v_lshlrev_b32_e32 v40, 16, v107
	v_mul_f32_e32 v73, 0xbfb8aa3b, v40
	v_exp_f32_e32 v73, v73
	v_pk_mul_f32 v[104:105], v[112:113], v[110:111]
	v_and_b32_e32 v111, 0xffff0000, v41
	v_lshlrev_b32_e32 v110, 16, v41
	v_and_b32_e32 v41, 0xffff0000, v107
	v_add_f32_e32 v73, 1.0, v73
	v_rcp_f32_e32 v106, v73
	v_pk_fma_f32 v[44:45], v[72:73], v[110:111], v[44:45] op_sel_hi:[0,1,1]
	v_mul_f32_e32 v73, 0xbfb8aa3b, v41
	v_exp_f32_e32 v73, v73
	s_waitcnt vmcnt(0)
	v_mov_b32_e32 v94, v134
	v_mov_b32_e32 v95, v135
	v_mov_b32_e32 v88, v136
	v_mov_b32_e32 v89, v137
	v_lshlrev_b32_e32 v110, 16, v88
	v_and_b32_e32 v111, 0xffff0000, v88
	v_pk_mul_f32 v[42:43], v[42:43], v[104:105]
	v_add_f32_e32 v73, 1.0, v73
	v_rcp_f32_e32 v107, v73
	v_mul_f32_e32 v73, 0xbfb8aa3b, v110
	v_exp_f32_e32 v73, v73
	v_pk_mul_f32 v[104:105], v[42:43], v[42:43]
	v_pk_mul_f32 v[40:41], v[106:107], v[40:41]
	v_add_f32_e32 v73, 1.0, v73
	v_pk_mul_f32 v[40:41], v[44:45], v[40:41]
	v_and_b32_e32 v45, 0xffff0000, v94
	v_lshlrev_b32_e32 v44, 16, v94
	v_pk_fma_f32 v[44:45], v[72:73], v[44:45], v[46:47] op_sel_hi:[0,1,1]
	v_mul_f32_e32 v46, 0xbfb8aa3b, v111
	v_exp_f32_e32 v46, v46
	v_lshlrev_b32_e32 v94, 16, v89
	v_rcp_f32_e32 v112, v73
	v_mul_f32_e32 v73, 0xbfb8aa3b, v94
	v_add_f32_e32 v46, 1.0, v46
	v_rcp_f32_e32 v113, v46
	v_exp_f32_e32 v73, v73
	v_pk_mul_f32 v[106:107], v[40:41], v[40:41]
	v_pk_mul_f32 v[46:47], v[112:113], v[110:111]
	s_nop 0
	v_pk_mul_f32 v[44:45], v[44:45], v[46:47]
	v_and_b32_e32 v47, 0xffff0000, v95
	v_lshlrev_b32_e32 v46, 16, v95
	v_add_f32_e32 v73, 1.0, v73
	v_rcp_f32_e32 v88, v73
	v_pk_fma_f32 v[46:47], v[72:73], v[46:47], v[48:49] op_sel_hi:[0,1,1]
	v_add_f32_e32 v73, v76, v77
	v_add_f32_e32 v73, v78, v73
	v_add_f32_e32 v73, v79, v73
	v_add_f32_e32 v73, v80, v73
	v_add_f32_e32 v73, v81, v73
	v_add_f32_e32 v73, v82, v73
	v_add_f32_e32 v73, v83, v73
	v_add_f32_e32 v73, v84, v73
	v_add_f32_e32 v73, v85, v73
	v_add_f32_e32 v73, v86, v73
	v_add_f32_e32 v73, v87, v73
	v_add_f32_e32 v73, v90, v73
	v_add_f32_e32 v73, v91, v73
	v_add_f32_e32 v73, v92, v73
	v_add_f32_e32 v73, v93, v73
	v_and_b32_e32 v95, 0xffff0000, v89
	v_add_f32_e32 v73, v96, v73
	v_mul_f32_e32 v48, 0xbfb8aa3b, v95
	v_add_f32_e32 v73, v97, v73
	v_exp_f32_e32 v48, v48
	v_add_f32_e32 v73, v98, v73
	v_add_f32_e32 v73, v99, v73
	v_add_f32_e32 v73, v100, v73
	v_add_f32_e32 v73, v101, v73
	v_add_f32_e32 v48, 1.0, v48
	v_add_f32_e32 v73, v102, v73
	v_rcp_f32_e32 v89, v48
	v_add_f32_e32 v73, v103, v73
	v_add_f32_e32 v73, v104, v73
	v_add_f32_e32 v73, v105, v73
	v_add_f32_e32 v73, v106, v73
	v_pk_mul_f32 v[110:111], v[44:45], v[44:45]
	v_pk_mul_f32 v[48:49], v[88:89], v[94:95]
	v_add_f32_e32 v73, v107, v73
	v_pk_mul_f32 v[46:47], v[46:47], v[48:49]
	v_add_f32_e32 v73, v110, v73
	v_pk_mul_f32 v[48:49], v[46:47], v[46:47]
	v_add_f32_e32 v73, v111, v73
	v_add_f32_e32 v48, v48, v73
	v_add_f32_e32 v48, v49, v48
	ds_bpermute_b32 v49, v175, v48
	s_and_saveexec_b64 s[2:3], s[8:9]
	s_cbranch_execz .LBB0_127
	s_waitcnt lgkmcnt(0)
	v_add_f32_e32 v48, v48, v49
	ds_write_b32 v184, v48 offset:34816
.LBB0_127:
	s_or_b64 exec, exec, s[2:3]
	v_add_u32_e32 v48, v108, v185
	v_readlane_b32 s2, v255, 8
	s_waitcnt lgkmcnt(0)
	v_ashrrev_i32_e32 v49, 31, v48
	v_readlane_b32 s3, v255, 9
	v_mov_b32_e32 v73, v72
	s_nop 0
	v_lshl_add_u64 v[76:77], s[2:3], 0, v[48:49]
	v_lshl_add_u64 v[48:49], s[0:1], 0, v[48:49]
	v_lshlrev_b64 v[76:77], 13, v[76:77]
	v_lshlrev_b64 v[48:49], 12, v[48:49]
	v_lshl_add_u64 v[74:75], v[74:75], 0, v[76:77]
	v_lshl_add_u64 v[48:49], v[66:67], 0, v[48:49]
	v_lshl_add_u64 v[94:95], v[74:75], 0, v[68:69]
	v_lshl_add_u64 v[86:87], v[48:49], 0, v[68:69]
	global_load_dwordx2 v[200:201], v[94:95], off
	global_load_dwordx2 v[202:203], v[86:87], off
	global_load_dwordx2 v[204:205], v[94:95], off offset:16
	global_load_dwordx2 v[206:207], v[86:87], off offset:16
	global_load_dwordx2 v[208:209], v[94:95], off offset:32
	global_load_dwordx2 v[210:211], v[86:87], off offset:32
	global_load_dwordx2 v[212:213], v[94:95], off offset:48
	global_load_dwordx2 v[214:215], v[86:87], off offset:48
	global_load_dwordx2 v[222:223], v[94:95], off offset:64
	global_load_dwordx2 v[224:225], v[86:87], off offset:64
	global_load_dwordx2 v[226:227], v[94:95], off offset:80
	global_load_dwordx2 v[228:229], v[86:87], off offset:80
	global_load_dwordx2 v[130:131], v[94:95], off offset:96
	global_load_dwordx2 v[132:133], v[86:87], off offset:96
	global_load_dwordx2 v[134:135], v[94:95], off offset:112
	global_load_dwordx2 v[136:137], v[86:87], off offset:112
	s_waitcnt vmcnt(15)
	v_mov_b32_e32 v76, v200
	v_mov_b32_e32 v77, v201
	v_and_b32_e32 v49, 0xffff0000, v76
	v_lshlrev_b32_e32 v48, 16, v76
	s_waitcnt vmcnt(14)
	v_mov_b32_e32 v78, v202
	v_mov_b32_e32 v79, v203
	v_and_b32_e32 v75, 0xffff0000, v78
	v_lshlrev_b32_e32 v74, 16, v78
	v_mul_f32_e32 v69, 0xbfb8aa3b, v74
	v_pk_fma_f32 v[18:19], v[72:73], v[48:49], v[18:19]
	v_mul_f32_e32 v48, 0xbfb8aa3b, v75
	v_exp_f32_e32 v69, v69
	v_exp_f32_e32 v48, v48
	v_lshlrev_b32_e32 v76, 16, v79
	v_add_f32_e32 v69, 1.0, v69
	v_add_f32_e32 v48, 1.0, v48
	v_rcp_f32_e32 v80, v69
	v_rcp_f32_e32 v81, v48
	v_mul_f32_e32 v69, 0xbfb8aa3b, v76
	v_exp_f32_e32 v69, v69
	v_pk_mul_f32 v[48:49], v[80:81], v[74:75]
	s_nop 0
	v_pk_mul_f32 v[48:49], v[18:19], v[48:49]
	v_and_b32_e32 v19, 0xffff0000, v77
	v_lshlrev_b32_e32 v18, 16, v77
	v_and_b32_e32 v77, 0xffff0000, v79
	v_pk_fma_f32 v[18:19], v[72:73], v[18:19], v[20:21]
	v_mul_f32_e32 v20, 0xbfb8aa3b, v77
	v_exp_f32_e32 v20, v20
	v_add_f32_e32 v69, 1.0, v69
	v_rcp_f32_e32 v78, v69
	v_pk_mul_f32 v[74:75], v[48:49], v[48:49]
	v_add_f32_e32 v20, 1.0, v20
	v_rcp_f32_e32 v79, v20
	s_nop 0
	v_pk_mul_f32 v[20:21], v[78:79], v[76:77]
	s_nop 0
	v_pk_mul_f32 v[18:19], v[18:19], v[20:21]
	v_pk_mul_f32 v[76:77], v[18:19], v[18:19]
	s_waitcnt vmcnt(13)
	v_mov_b32_e32 v20, v204
	v_mov_b32_e32 v21, v205
	v_and_b32_e32 v79, 0xffff0000, v20
	s_waitcnt vmcnt(12)
	v_mov_b32_e32 v80, v206
	v_mov_b32_e32 v81, v207
	v_lshlrev_b32_e32 v82, 16, v80
	v_lshlrev_b32_e32 v78, 16, v20
	v_mul_f32_e32 v20, 0xbfb8aa3b, v82
	v_exp_f32_e32 v20, v20
	v_and_b32_e32 v83, 0xffff0000, v80
	v_pk_fma_f32 v[22:23], v[72:73], v[78:79], v[22:23]
	v_add_f32_e32 v20, 1.0, v20
	v_rcp_f32_e32 v84, v20
	v_mul_f32_e32 v20, 0xbfb8aa3b, v83
	v_exp_f32_e32 v20, v20
	s_nop 0
	v_add_f32_e32 v20, 1.0, v20
	v_rcp_f32_e32 v85, v20
	v_lshlrev_b32_e32 v20, 16, v81
	v_mul_f32_e32 v69, 0xbfb8aa3b, v20
	v_exp_f32_e32 v69, v69
	v_pk_mul_f32 v[78:79], v[84:85], v[82:83]
	v_and_b32_e32 v83, 0xffff0000, v21
	v_lshlrev_b32_e32 v82, 16, v21
	v_and_b32_e32 v21, 0xffff0000, v81
	v_add_f32_e32 v69, 1.0, v69
	v_rcp_f32_e32 v80, v69
	v_mul_f32_e32 v69, 0xbfb8aa3b, v21
	v_exp_f32_e32 v69, v69
	v_pk_fma_f32 v[24:25], v[72:73], v[82:83], v[24:25]
	v_pk_mul_f32 v[22:23], v[22:23], v[78:79]
	v_add_f32_e32 v69, 1.0, v69
	v_rcp_f32_e32 v81, v69
	v_pk_mul_f32 v[78:79], v[22:23], v[22:23]
	v_pk_mul_f32 v[20:21], v[80:81], v[20:21]
	s_nop 0
	v_pk_mul_f32 v[20:21], v[24:25], v[20:21]
	v_pk_mul_f32 v[80:81], v[20:21], v[20:21]
	s_waitcnt vmcnt(11)
	v_mov_b32_e32 v24, v208
	v_mov_b32_e32 v25, v209
	v_and_b32_e32 v83, 0xffff0000, v24
	s_waitcnt vmcnt(10)
	v_mov_b32_e32 v84, v210
	v_mov_b32_e32 v85, v211
	v_lshlrev_b32_e32 v88, 16, v84
	v_lshlrev_b32_e32 v82, 16, v24
	v_mul_f32_e32 v24, 0xbfb8aa3b, v88
	v_exp_f32_e32 v24, v24
	v_and_b32_e32 v89, 0xffff0000, v84
	v_pk_fma_f32 v[26:27], v[72:73], v[82:83], v[26:27]
	v_add_f32_e32 v24, 1.0, v24
	v_rcp_f32_e32 v90, v24
	v_mul_f32_e32 v24, 0xbfb8aa3b, v89
	v_exp_f32_e32 v24, v24
	s_nop 0
	v_add_f32_e32 v24, 1.0, v24
	v_rcp_f32_e32 v91, v24
	v_lshlrev_b32_e32 v24, 16, v85
	v_mul_f32_e32 v69, 0xbfb8aa3b, v24
	v_exp_f32_e32 v69, v69
	v_pk_mul_f32 v[82:83], v[90:91], v[88:89]
	v_and_b32_e32 v89, 0xffff0000, v25
	v_lshlrev_b32_e32 v88, 16, v25
	v_and_b32_e32 v25, 0xffff0000, v85
	v_add_f32_e32 v69, 1.0, v69
	v_rcp_f32_e32 v84, v69
	v_mul_f32_e32 v69, 0xbfb8aa3b, v25
	v_exp_f32_e32 v69, v69
	v_pk_fma_f32 v[28:29], v[72:73], v[88:89], v[28:29]
	v_pk_mul_f32 v[26:27], v[26:27], v[82:83]
	v_add_f32_e32 v69, 1.0, v69
	v_rcp_f32_e32 v85, v69
	v_pk_mul_f32 v[82:83], v[26:27], v[26:27]
	v_pk_mul_f32 v[24:25], v[84:85], v[24:25]
	s_nop 0
	v_pk_mul_f32 v[24:25], v[28:29], v[24:25]
	v_pk_mul_f32 v[84:85], v[24:25], v[24:25]
	s_waitcnt vmcnt(9)
	v_mov_b32_e32 v28, v212
	v_mov_b32_e32 v29, v213
	v_and_b32_e32 v89, 0xffff0000, v28
	s_waitcnt vmcnt(8)
	v_mov_b32_e32 v90, v214
	v_mov_b32_e32 v91, v215
	v_lshlrev_b32_e32 v92, 16, v90
	v_lshlrev_b32_e32 v88, 16, v28
	v_mul_f32_e32 v28, 0xbfb8aa3b, v92
	v_exp_f32_e32 v28, v28
	v_and_b32_e32 v93, 0xffff0000, v90
	v_pk_fma_f32 v[30:31], v[72:73], v[88:89], v[30:31]
	v_add_f32_e32 v28, 1.0, v28
	v_rcp_f32_e32 v96, v28
	v_mul_f32_e32 v28, 0xbfb8aa3b, v93
	v_exp_f32_e32 v28, v28
	s_nop 0
	v_add_f32_e32 v28, 1.0, v28
	v_rcp_f32_e32 v97, v28
	v_lshlrev_b32_e32 v28, 16, v91
	v_mul_f32_e32 v69, 0xbfb8aa3b, v28
	v_exp_f32_e32 v69, v69
	v_pk_mul_f32 v[88:89], v[96:97], v[92:93]
	v_and_b32_e32 v93, 0xffff0000, v29
	v_lshlrev_b32_e32 v92, 16, v29
	v_and_b32_e32 v29, 0xffff0000, v91
	v_add_f32_e32 v69, 1.0, v69
	v_rcp_f32_e32 v90, v69
	v_mul_f32_e32 v69, 0xbfb8aa3b, v29
	v_exp_f32_e32 v69, v69
	v_pk_fma_f32 v[32:33], v[72:73], v[92:93], v[32:33]
	v_pk_mul_f32 v[30:31], v[30:31], v[88:89]
	v_add_f32_e32 v69, 1.0, v69
	v_rcp_f32_e32 v91, v69
	v_pk_mul_f32 v[88:89], v[30:31], v[30:31]
	v_pk_mul_f32 v[28:29], v[90:91], v[28:29]
	s_nop 0
	v_pk_mul_f32 v[28:29], v[32:33], v[28:29]
	s_waitcnt vmcnt(7)
	v_mov_b32_e32 v96, v222
	v_mov_b32_e32 v97, v223
	v_and_b32_e32 v33, 0xffff0000, v96
	v_lshlrev_b32_e32 v32, 16, v96
	s_waitcnt vmcnt(6)
	v_mov_b32_e32 v98, v224
	v_mov_b32_e32 v99, v225
	v_and_b32_e32 v93, 0xffff0000, v98
	v_lshlrev_b32_e32 v92, 16, v98
	v_mul_f32_e32 v69, 0xbfb8aa3b, v92
	v_pk_fma_f32 v[2:3], v[72:73], v[32:33], v[2:3]
	v_mul_f32_e32 v32, 0xbfb8aa3b, v93
	v_exp_f32_e32 v69, v69
	v_exp_f32_e32 v32, v32
	v_lshlrev_b32_e32 v96, 16, v99
	v_pk_mul_f32 v[90:91], v[28:29], v[28:29]
	v_add_f32_e32 v69, 1.0, v69
	v_add_f32_e32 v32, 1.0, v32
	v_rcp_f32_e32 v100, v69
	v_rcp_f32_e32 v101, v32
	v_mul_f32_e32 v69, 0xbfb8aa3b, v96
	v_exp_f32_e32 v69, v69
	v_pk_mul_f32 v[32:33], v[100:101], v[92:93]
	s_nop 0
	v_pk_mul_f32 v[32:33], v[2:3], v[32:33]
	v_and_b32_e32 v3, 0xffff0000, v97
	v_lshlrev_b32_e32 v2, 16, v97
	v_and_b32_e32 v97, 0xffff0000, v99
	v_pk_fma_f32 v[2:3], v[72:73], v[2:3], v[4:5]
	v_mul_f32_e32 v4, 0xbfb8aa3b, v97
	v_exp_f32_e32 v4, v4
	v_add_f32_e32 v69, 1.0, v69
	v_rcp_f32_e32 v98, v69
	v_pk_mul_f32 v[92:93], v[32:33], v[32:33]
	v_add_f32_e32 v4, 1.0, v4
	v_rcp_f32_e32 v99, v4
	s_nop 0
	v_pk_mul_f32 v[4:5], v[98:99], v[96:97]
	s_nop 0
	v_pk_mul_f32 v[2:3], v[2:3], v[4:5]
	v_pk_mul_f32 v[96:97], v[2:3], v[2:3]
	s_waitcnt vmcnt(5)
	v_mov_b32_e32 v4, v226
	v_mov_b32_e32 v5, v227
	v_and_b32_e32 v99, 0xffff0000, v4
	s_waitcnt vmcnt(4)
	v_mov_b32_e32 v100, v228
	v_mov_b32_e32 v101, v229
	v_lshlrev_b32_e32 v102, 16, v100
	v_lshlrev_b32_e32 v98, 16, v4
	v_mul_f32_e32 v4, 0xbfb8aa3b, v102
	v_exp_f32_e32 v4, v4
	v_and_b32_e32 v103, 0xffff0000, v100
	v_pk_fma_f32 v[6:7], v[72:73], v[98:99], v[6:7]
	v_add_f32_e32 v4, 1.0, v4
	v_rcp_f32_e32 v104, v4
	v_mul_f32_e32 v4, 0xbfb8aa3b, v103
	v_exp_f32_e32 v4, v4
	s_nop 0
	v_add_f32_e32 v4, 1.0, v4
	v_rcp_f32_e32 v105, v4
	v_lshlrev_b32_e32 v4, 16, v101
	v_mul_f32_e32 v69, 0xbfb8aa3b, v4
	v_exp_f32_e32 v69, v69
	v_pk_mul_f32 v[98:99], v[104:105], v[102:103]
	v_and_b32_e32 v103, 0xffff0000, v5
	v_lshlrev_b32_e32 v102, 16, v5
	v_and_b32_e32 v5, 0xffff0000, v101
	v_add_f32_e32 v69, 1.0, v69
	v_rcp_f32_e32 v100, v69
	v_mul_f32_e32 v69, 0xbfb8aa3b, v5
	v_exp_f32_e32 v69, v69
	v_pk_fma_f32 v[8:9], v[72:73], v[102:103], v[8:9]
	v_pk_mul_f32 v[6:7], v[6:7], v[98:99]
	v_add_f32_e32 v69, 1.0, v69
	v_rcp_f32_e32 v101, v69
	v_pk_mul_f32 v[98:99], v[6:7], v[6:7]
	v_pk_mul_f32 v[4:5], v[100:101], v[4:5]
	s_nop 0
	v_pk_mul_f32 v[4:5], v[8:9], v[4:5]
	s_nop 0
	s_nop 0
	v_pk_mul_f32 v[100:101], v[4:5], v[4:5]
	s_waitcnt vmcnt(3)
	v_mov_b32_e32 v8, v130
	v_mov_b32_e32 v9, v131
	v_and_b32_e32 v103, 0xffff0000, v8
	s_waitcnt vmcnt(2)
	v_mov_b32_e32 v104, v132
	v_mov_b32_e32 v105, v133
	v_lshlrev_b32_e32 v106, 16, v104
	v_lshlrev_b32_e32 v102, 16, v8
	v_mul_f32_e32 v8, 0xbfb8aa3b, v106
	v_exp_f32_e32 v8, v8
	v_and_b32_e32 v107, 0xffff0000, v104
	v_pk_fma_f32 v[10:11], v[72:73], v[102:103], v[10:11]
	v_add_f32_e32 v8, 1.0, v8
	v_rcp_f32_e32 v108, v8
	v_mul_f32_e32 v8, 0xbfb8aa3b, v107
	v_exp_f32_e32 v8, v8
	s_nop 0
	v_add_f32_e32 v8, 1.0, v8
	v_rcp_f32_e32 v109, v8
	v_lshlrev_b32_e32 v8, 16, v105
	v_mul_f32_e32 v69, 0xbfb8aa3b, v8
	v_exp_f32_e32 v69, v69
	v_pk_mul_f32 v[102:103], v[108:109], v[106:107]
	v_and_b32_e32 v107, 0xffff0000, v9
	v_lshlrev_b32_e32 v106, 16, v9
	v_and_b32_e32 v9, 0xffff0000, v105
	v_add_f32_e32 v69, 1.0, v69
	v_rcp_f32_e32 v104, v69
	v_mul_f32_e32 v69, 0xbfb8aa3b, v9
	v_exp_f32_e32 v69, v69
	v_pk_fma_f32 v[12:13], v[72:73], v[106:107], v[12:13]
	s_waitcnt vmcnt(0)
	v_mov_b32_e32 v94, v134
	v_mov_b32_e32 v95, v135
	v_mov_b32_e32 v86, v136
	v_mov_b32_e32 v87, v137
	v_lshlrev_b32_e32 v106, 16, v86
	v_and_b32_e32 v107, 0xffff0000, v86
	v_add_f32_e32 v69, 1.0, v69
	v_rcp_f32_e32 v105, v69
	v_mul_f32_e32 v69, 0xbfb8aa3b, v106
	v_exp_f32_e32 v69, v69
	v_pk_mul_f32 v[10:11], v[10:11], v[102:103]
	v_pk_mul_f32 v[8:9], v[104:105], v[8:9]
	v_pk_mul_f32 v[102:103], v[10:11], v[10:11]
	v_pk_mul_f32 v[8:9], v[12:13], v[8:9]
	v_and_b32_e32 v13, 0xffff0000, v94
	v_lshlrev_b32_e32 v12, 16, v94
	v_add_f32_e32 v69, 1.0, v69
	v_lshlrev_b32_e32 v94, 16, v87
	v_rcp_f32_e32 v108, v69
	v_mul_f32_e32 v69, 0xbfb8aa3b, v94
	v_exp_f32_e32 v69, v69
	v_pk_fma_f32 v[12:13], v[72:73], v[12:13], v[14:15]
	v_mul_f32_e32 v14, 0xbfb8aa3b, v107
	v_exp_f32_e32 v14, v14
	v_add_f32_e32 v69, 1.0, v69
	v_rcp_f32_e32 v86, v69
	v_add_f32_e32 v69, v74, v75
	v_add_f32_e32 v69, v76, v69
	v_add_f32_e32 v69, v77, v69
	v_add_f32_e32 v69, v78, v69
	v_add_f32_e32 v69, v79, v69
	v_add_f32_e32 v69, v80, v69
	v_add_f32_e32 v69, v81, v69
	v_add_f32_e32 v69, v82, v69
	v_add_f32_e32 v69, v83, v69
	v_add_f32_e32 v14, 1.0, v14
	v_add_f32_e32 v69, v84, v69
	v_rcp_f32_e32 v109, v14
	v_add_f32_e32 v69, v85, v69
	v_add_f32_e32 v69, v88, v69
	v_add_f32_e32 v69, v89, v69
	v_add_f32_e32 v69, v90, v69
	v_pk_mul_f32 v[14:15], v[108:109], v[106:107]
	v_add_f32_e32 v69, v91, v69
	v_pk_mul_f32 v[12:13], v[12:13], v[14:15]
	v_and_b32_e32 v15, 0xffff0000, v95
	v_lshlrev_b32_e32 v14, 16, v95
	v_and_b32_e32 v95, 0xffff0000, v87
	v_add_f32_e32 v69, v92, v69
	v_pk_fma_f32 v[14:15], v[72:73], v[14:15], v[16:17]
	v_mul_f32_e32 v16, 0xbfb8aa3b, v95
	v_add_f32_e32 v69, v93, v69
	v_exp_f32_e32 v16, v16
	v_add_f32_e32 v69, v96, v69
	v_add_f32_e32 v69, v97, v69
	v_add_f32_e32 v69, v98, v69
	v_add_f32_e32 v69, v99, v69
	v_add_f32_e32 v16, 1.0, v16
	v_add_f32_e32 v69, v100, v69
	v_rcp_f32_e32 v87, v16
	v_add_f32_e32 v69, v101, v69
	v_add_f32_e32 v69, v102, v69
	v_pk_mul_f32 v[104:105], v[8:9], v[8:9]
	v_add_f32_e32 v69, v103, v69
	v_add_f32_e32 v69, v104, v69
	v_pk_mul_f32 v[106:107], v[12:13], v[12:13]
	v_pk_mul_f32 v[16:17], v[86:87], v[94:95]
	v_add_f32_e32 v69, v105, v69
	v_pk_mul_f32 v[14:15], v[14:15], v[16:17]
	v_add_f32_e32 v69, v106, v69
	v_pk_mul_f32 v[16:17], v[14:15], v[14:15]
	v_add_f32_e32 v69, v107, v69
	v_add_f32_e32 v16, v16, v69
	v_add_f32_e32 v16, v17, v16
	ds_bpermute_b32 v17, v175, v16
	s_and_saveexec_b64 s[2:3], s[8:9]
	v_readlane_b32 s42, v254, 59
	v_readlane_b32 s43, v254, 60
	s_movk_i32 s37, 0x1000
	s_movk_i32 s36, 0x1ff
	s_mov_b32 s47, 0x7f800000
	s_mov_b32 s49, 0x20000
	s_cbranch_execz .LBB0_129
	s_waitcnt lgkmcnt(0)
	v_add_f32_e32 v16, v16, v17
	ds_write_b32 v184, v16 offset:34944
